# SwiGLU GEMM epilogue: silu(a)*b in batches with packed mul/add (same arithmetic)
# speedup vs baseline: 1.0166x; 1.0014x over previous
;     __device__ __forceinline__ void operator()(const f32x4 (&acc)[2][2][4][2], const pg8::Unit& u, int wr, int wc, int fr, int fq) const {
;         const int row0 = u.pm * 256 + wr * 64 + fr, col0 = (u.pn * 256 + wc * 32 + 8 * fq) >> 1;
; #pragma unroll
;         for (int ai = 0; ai < 2; ++ai)
; #pragma unroll
;             for (int m = 0; m < 4; ++m) {
;                 bf16_t* rowp = O + (size_t)(row0 + ai * 128 + m * 16) * FFH + col0;
.LBB0_46:
	v_lshl_or_b32 v158, s16, 8, v144
	v_lshl_add_u32 v146, s48, 8, v142
	s_movk_i32 s4, 0x1600
	v_mov_b32_e32 v172, 0xbfb8aa3b
	v_mov_b32_e32 v173, 0xbfb8aa3b
	v_mad_u32_u24 v160, v146, s4, v158
	v_add_u32_e32 v161, 0x16000, v160
	v_add_u32_e32 v162, 0x2c000, v160
	v_add_u32_e32 v163, 0x42000, v160
	v_add_u32_e32 v164, 0xb0000, v160
	v_add_u32_e32 v165, 0xc6000, v160
	v_add_u32_e32 v166, 0xdc000, v160
	v_add_u32_e32 v167, 0xf2000, v160

; __device__ __forceinline__ unsigned cvt_pk_bf16(float lo, float hi) { unsigned r; asm volatile("v_cvt_pk_bf16_f32 %0, %1, %2" : "=v"(r) : "v"(lo), "v"(hi)); return r; }
; __device__ __forceinline__ float silu_f(float v) { return v * __builtin_amdgcn_rcpf(1.f + __builtin_amdgcn_exp2f(-v * LOG2E)); }
;     __device__ __forceinline__ void operator()(const f32x4 (&acc)[2][2][4][2], const pg8::Unit& u, int wr, int wc, int fr, int fq) const {
;     ...
;                 bf16_t* rowp = O + (size_t)(row0 + ai * 128 + m * 16) * FFH + col0;
; #pragma unroll
;                 for (int bj = 0; bj < 2; ++bj) {
;                     const f32x4 a = acc[ai][bj][m][0], b = acc[ai][bj][m][1];
;                     u32x2 w; w.x = cvt_pk_bf16(silu_f(a[0]) * b[0], silu_f(a[1]) * b[1]); w.y = cvt_pk_bf16(silu_f(a[2]) * b[2], silu_f(a[3]) * b[3]);
;                     *(u32x2*)(rowp + bj * 64) = w;
	v_pk_mul_f32 v[146:147], v[124:125], v[172:173]
	v_pk_mul_f32 v[148:149], v[126:127], v[172:173]
	v_pk_mul_f32 v[150:151], v[116:117], v[172:173]
	v_pk_mul_f32 v[152:153], v[118:119], v[172:173]
	v_exp_f32_e32 v146, v146
	v_exp_f32_e32 v147, v147
	v_exp_f32_e32 v148, v148
	v_exp_f32_e32 v149, v149
	v_exp_f32_e32 v150, v150
	v_exp_f32_e32 v151, v151
	v_exp_f32_e32 v152, v152
	v_exp_f32_e32 v153, v153
	v_pk_add_f32 v[146:147], v[146:147], 1.0 op_sel_hi:[1,0]
	v_pk_add_f32 v[148:149], v[148:149], 1.0 op_sel_hi:[1,0]
	v_pk_add_f32 v[150:151], v[150:151], 1.0 op_sel_hi:[1,0]
	v_pk_add_f32 v[152:153], v[152:153], 1.0 op_sel_hi:[1,0]
	v_rcp_f32_e32 v146, v146
	v_rcp_f32_e32 v147, v147
	v_rcp_f32_e32 v148, v148
	v_rcp_f32_e32 v149, v149
	v_rcp_f32_e32 v150, v150
	v_rcp_f32_e32 v151, v151
	v_rcp_f32_e32 v152, v152
	v_rcp_f32_e32 v153, v153
	v_pk_mul_f32 v[124:125], v[124:125], v[146:147]
	v_pk_mul_f32 v[126:127], v[126:127], v[148:149]
	v_pk_mul_f32 v[116:117], v[116:117], v[150:151]
	v_pk_mul_f32 v[118:119], v[118:119], v[152:153]
	v_pk_mul_f32 v[120:121], v[120:121], v[124:125]
	v_pk_mul_f32 v[122:123], v[122:123], v[126:127]
	v_pk_mul_f32 v[112:113], v[112:113], v[116:117]
	v_pk_mul_f32 v[114:115], v[114:115], v[118:119]
	v_cvt_pk_bf16_f32 v154, v120, v121
	v_cvt_pk_bf16_f32 v156, v112, v113
	v_cvt_pk_bf16_f32 v155, v122, v123
	v_cvt_pk_bf16_f32 v157, v114, v115
	global_store_dwordx2 v160, v[154:155], s[18:19]
	global_store_dwordx2 v160, v[156:157], s[18:19] offset:128
	v_pk_mul_f32 v[146:147], v[108:109], v[172:173]
	v_pk_mul_f32 v[148:149], v[110:111], v[172:173]
	v_pk_mul_f32 v[150:151], v[100:101], v[172:173]
	v_pk_mul_f32 v[152:153], v[102:103], v[172:173]
	v_exp_f32_e32 v146, v146
	v_exp_f32_e32 v147, v147
	v_exp_f32_e32 v148, v148
	v_exp_f32_e32 v149, v149
	v_exp_f32_e32 v150, v150
	v_exp_f32_e32 v151, v151
	v_exp_f32_e32 v152, v152
	v_exp_f32_e32 v153, v153
	v_pk_add_f32 v[146:147], v[146:147], 1.0 op_sel_hi:[1,0]
	v_pk_add_f32 v[148:149], v[148:149], 1.0 op_sel_hi:[1,0]
	v_pk_add_f32 v[150:151], v[150:151], 1.0 op_sel_hi:[1,0]
	v_pk_add_f32 v[152:153], v[152:153], 1.0 op_sel_hi:[1,0]
	v_rcp_f32_e32 v146, v146
	v_rcp_f32_e32 v147, v147
	v_rcp_f32_e32 v148, v148
	v_rcp_f32_e32 v149, v149
	v_rcp_f32_e32 v150, v150
	v_rcp_f32_e32 v151, v151
	v_rcp_f32_e32 v152, v152
	v_rcp_f32_e32 v153, v153
	v_pk_mul_f32 v[108:109], v[108:109], v[146:147]
	v_pk_mul_f32 v[110:111], v[110:111], v[148:149]
	v_pk_mul_f32 v[100:101], v[100:101], v[150:151]
	v_pk_mul_f32 v[102:103], v[102:103], v[152:153]
	v_pk_mul_f32 v[104:105], v[104:105], v[108:109]
	v_pk_mul_f32 v[106:107], v[106:107], v[110:111]
	v_pk_mul_f32 v[96:97], v[96:97], v[100:101]
	v_pk_mul_f32 v[98:99], v[98:99], v[102:103]
	v_cvt_pk_bf16_f32 v168, v104, v105
	v_cvt_pk_bf16_f32 v170, v96, v97
	v_cvt_pk_bf16_f32 v169, v106, v107
	v_cvt_pk_bf16_f32 v171, v98, v99
	global_store_dwordx2 v161, v[168:169], s[18:19]
	global_store_dwordx2 v161, v[170:171], s[18:19] offset:128
	v_pk_mul_f32 v[146:147], v[92:93], v[172:173]
	v_pk_mul_f32 v[148:149], v[94:95], v[172:173]
	v_pk_mul_f32 v[150:151], v[84:85], v[172:173]
	v_pk_mul_f32 v[152:153], v[86:87], v[172:173]
	v_exp_f32_e32 v146, v146
	v_exp_f32_e32 v147, v147
	v_exp_f32_e32 v148, v148
	v_exp_f32_e32 v149, v149
	v_exp_f32_e32 v150, v150
	v_exp_f32_e32 v151, v151
	v_exp_f32_e32 v152, v152
	v_exp_f32_e32 v153, v153
	v_pk_add_f32 v[146:147], v[146:147], 1.0 op_sel_hi:[1,0]
	v_pk_add_f32 v[148:149], v[148:149], 1.0 op_sel_hi:[1,0]
	v_pk_add_f32 v[150:151], v[150:151], 1.0 op_sel_hi:[1,0]
	v_pk_add_f32 v[152:153], v[152:153], 1.0 op_sel_hi:[1,0]
	v_rcp_f32_e32 v146, v146
	v_rcp_f32_e32 v147, v147
	v_rcp_f32_e32 v148, v148
	v_rcp_f32_e32 v149, v149
	v_rcp_f32_e32 v150, v150
	v_rcp_f32_e32 v151, v151
	v_rcp_f32_e32 v152, v152
	v_rcp_f32_e32 v153, v153
	v_pk_mul_f32 v[92:93], v[92:93], v[146:147]
	v_pk_mul_f32 v[94:95], v[94:95], v[148:149]
	v_pk_mul_f32 v[84:85], v[84:85], v[150:151]
	v_pk_mul_f32 v[86:87], v[86:87], v[152:153]
	v_pk_mul_f32 v[88:89], v[88:89], v[92:93]
	v_pk_mul_f32 v[90:91], v[90:91], v[94:95]
	v_pk_mul_f32 v[80:81], v[80:81], v[84:85]
	v_pk_mul_f32 v[82:83], v[82:83], v[86:87]
	v_cvt_pk_bf16_f32 v154, v88, v89
	v_cvt_pk_bf16_f32 v156, v80, v81
	v_cvt_pk_bf16_f32 v155, v90, v91
	v_cvt_pk_bf16_f32 v157, v82, v83
	global_store_dwordx2 v162, v[154:155], s[18:19]
	global_store_dwordx2 v162, v[156:157], s[18:19] offset:128
	v_pk_mul_f32 v[146:147], v[76:77], v[172:173]
	v_pk_mul_f32 v[148:149], v[78:79], v[172:173]
	v_pk_mul_f32 v[150:151], v[68:69], v[172:173]
	v_pk_mul_f32 v[152:153], v[70:71], v[172:173]
	v_exp_f32_e32 v146, v146
	v_exp_f32_e32 v147, v147
	v_exp_f32_e32 v148, v148
	v_exp_f32_e32 v149, v149
	v_exp_f32_e32 v150, v150
	v_exp_f32_e32 v151, v151
	v_exp_f32_e32 v152, v152
	v_exp_f32_e32 v153, v153
	v_pk_add_f32 v[146:147], v[146:147], 1.0 op_sel_hi:[1,0]
	v_pk_add_f32 v[148:149], v[148:149], 1.0 op_sel_hi:[1,0]
	v_pk_add_f32 v[150:151], v[150:151], 1.0 op_sel_hi:[1,0]
	v_pk_add_f32 v[152:153], v[152:153], 1.0 op_sel_hi:[1,0]
	v_rcp_f32_e32 v146, v146
	v_rcp_f32_e32 v147, v147
	v_rcp_f32_e32 v148, v148
	v_rcp_f32_e32 v149, v149
	v_rcp_f32_e32 v150, v150
	v_rcp_f32_e32 v151, v151
	v_rcp_f32_e32 v152, v152
	v_rcp_f32_e32 v153, v153
	v_pk_mul_f32 v[76:77], v[76:77], v[146:147]
	v_pk_mul_f32 v[78:79], v[78:79], v[148:149]
	v_pk_mul_f32 v[68:69], v[68:69], v[150:151]
	v_pk_mul_f32 v[70:71], v[70:71], v[152:153]
	v_pk_mul_f32 v[72:73], v[72:73], v[76:77]
	v_pk_mul_f32 v[74:75], v[74:75], v[78:79]
	v_pk_mul_f32 v[64:65], v[64:65], v[68:69]
	v_pk_mul_f32 v[66:67], v[66:67], v[70:71]
	v_cvt_pk_bf16_f32 v168, v72, v73
	v_cvt_pk_bf16_f32 v170, v64, v65
; __device__ __forceinline__ unsigned cvt_pk_bf16(float lo, float hi) { unsigned r; asm volatile("v_cvt_pk_bf16_f32 %0, %1, %2" : "=v"(r) : "v"(lo), "v"(hi)); return r; }
; __device__ __forceinline__ float silu_f(float v) { return v * __builtin_amdgcn_rcpf(1.f + __builtin_amdgcn_exp2f(-v * LOG2E)); }
; template <class Epi, class Sched, bool ALIGN_EPI = false, bool SP2 = false>
; __device__ __forceinline__ void gemm_phase(PG8_LAS unsigned char* lds, const Gemm g, const Sched& S, const Epi& E) {
;     ...
;         if (!has_next) break;
;     __device__ __forceinline__ void operator()(const f32x4 (&acc)[2][2][4][2], const pg8::Unit& u, int wr, int wc, int fr, int fq) const {
;     ...
;                 bf16_t* rowp = O + (size_t)(row0 + ai * 128 + m * 16) * FFH + col0;
; #pragma unroll
;                 for (int bj = 0; bj < 2; ++bj) {
;                     const f32x4 a = acc[ai][bj][m][0], b = acc[ai][bj][m][1];
;                     u32x2 w; w.x = cvt_pk_bf16(silu_f(a[0]) * b[0], silu_f(a[1]) * b[1]); w.y = cvt_pk_bf16(silu_f(a[2]) * b[2], silu_f(a[3]) * b[3]);
;                     *(u32x2*)(rowp + bj * 64) = w;
	v_cvt_pk_bf16_f32 v169, v74, v75
	v_cvt_pk_bf16_f32 v171, v66, v67
	global_store_dwordx2 v163, v[168:169], s[18:19]
	global_store_dwordx2 v163, v[170:171], s[18:19] offset:128
	v_pk_mul_f32 v[146:147], v[60:61], v[172:173]
	v_pk_mul_f32 v[148:149], v[62:63], v[172:173]
	v_pk_mul_f32 v[150:151], v[52:53], v[172:173]
	v_pk_mul_f32 v[152:153], v[54:55], v[172:173]
	v_exp_f32_e32 v146, v146
	v_exp_f32_e32 v147, v147
	v_exp_f32_e32 v148, v148
	v_exp_f32_e32 v149, v149
	v_exp_f32_e32 v150, v150
	v_exp_f32_e32 v151, v151
	v_exp_f32_e32 v152, v152
	v_exp_f32_e32 v153, v153
	v_pk_add_f32 v[146:147], v[146:147], 1.0 op_sel_hi:[1,0]
	v_pk_add_f32 v[148:149], v[148:149], 1.0 op_sel_hi:[1,0]
	v_pk_add_f32 v[150:151], v[150:151], 1.0 op_sel_hi:[1,0]
	v_pk_add_f32 v[152:153], v[152:153], 1.0 op_sel_hi:[1,0]
	v_rcp_f32_e32 v146, v146
	v_rcp_f32_e32 v147, v147
	v_rcp_f32_e32 v148, v148
	v_rcp_f32_e32 v149, v149
	v_rcp_f32_e32 v150, v150
	v_rcp_f32_e32 v151, v151
	v_rcp_f32_e32 v152, v152
	v_rcp_f32_e32 v153, v153
	v_pk_mul_f32 v[60:61], v[60:61], v[146:147]
	v_pk_mul_f32 v[62:63], v[62:63], v[148:149]
	v_pk_mul_f32 v[52:53], v[52:53], v[150:151]
	v_pk_mul_f32 v[54:55], v[54:55], v[152:153]
	v_pk_mul_f32 v[56:57], v[56:57], v[60:61]
	v_pk_mul_f32 v[58:59], v[58:59], v[62:63]
	v_pk_mul_f32 v[48:49], v[48:49], v[52:53]
	v_pk_mul_f32 v[50:51], v[50:51], v[54:55]
	v_cvt_pk_bf16_f32 v154, v56, v57
	v_cvt_pk_bf16_f32 v156, v48, v49
	v_cvt_pk_bf16_f32 v155, v58, v59
	v_cvt_pk_bf16_f32 v157, v50, v51
	global_store_dwordx2 v164, v[154:155], s[18:19]
	global_store_dwordx2 v164, v[156:157], s[18:19] offset:128
	v_pk_mul_f32 v[146:147], v[44:45], v[172:173]
	v_pk_mul_f32 v[148:149], v[46:47], v[172:173]
	v_pk_mul_f32 v[150:151], v[36:37], v[172:173]
	v_pk_mul_f32 v[152:153], v[38:39], v[172:173]
	v_exp_f32_e32 v146, v146
	v_exp_f32_e32 v147, v147
	v_exp_f32_e32 v148, v148
	v_exp_f32_e32 v149, v149
	v_exp_f32_e32 v150, v150
	v_exp_f32_e32 v151, v151
	v_exp_f32_e32 v152, v152
	v_exp_f32_e32 v153, v153
	v_pk_add_f32 v[146:147], v[146:147], 1.0 op_sel_hi:[1,0]
	v_pk_add_f32 v[148:149], v[148:149], 1.0 op_sel_hi:[1,0]
	v_pk_add_f32 v[150:151], v[150:151], 1.0 op_sel_hi:[1,0]
	v_pk_add_f32 v[152:153], v[152:153], 1.0 op_sel_hi:[1,0]
	v_rcp_f32_e32 v146, v146
	v_rcp_f32_e32 v147, v147
	v_rcp_f32_e32 v148, v148
	v_rcp_f32_e32 v149, v149
	v_rcp_f32_e32 v150, v150
	v_rcp_f32_e32 v151, v151
	v_rcp_f32_e32 v152, v152
	v_rcp_f32_e32 v153, v153
	v_pk_mul_f32 v[44:45], v[44:45], v[146:147]
	v_pk_mul_f32 v[46:47], v[46:47], v[148:149]
	v_pk_mul_f32 v[36:37], v[36:37], v[150:151]
	v_pk_mul_f32 v[38:39], v[38:39], v[152:153]
	v_pk_mul_f32 v[40:41], v[40:41], v[44:45]
	v_pk_mul_f32 v[42:43], v[42:43], v[46:47]
	v_pk_mul_f32 v[32:33], v[32:33], v[36:37]
	v_pk_mul_f32 v[34:35], v[34:35], v[38:39]
	v_cvt_pk_bf16_f32 v168, v40, v41
	v_cvt_pk_bf16_f32 v170, v32, v33
	v_cvt_pk_bf16_f32 v169, v42, v43
	v_cvt_pk_bf16_f32 v171, v34, v35
	global_store_dwordx2 v165, v[168:169], s[18:19]
	global_store_dwordx2 v165, v[170:171], s[18:19] offset:128
	v_pk_mul_f32 v[146:147], v[28:29], v[172:173]
	v_pk_mul_f32 v[148:149], v[30:31], v[172:173]
	v_pk_mul_f32 v[150:151], v[20:21], v[172:173]
	v_pk_mul_f32 v[152:153], v[22:23], v[172:173]
	v_exp_f32_e32 v146, v146
	v_exp_f32_e32 v147, v147
	v_exp_f32_e32 v148, v148
	v_exp_f32_e32 v149, v149
	v_exp_f32_e32 v150, v150
	v_exp_f32_e32 v151, v151
	v_exp_f32_e32 v152, v152
	v_exp_f32_e32 v153, v153
	v_pk_add_f32 v[146:147], v[146:147], 1.0 op_sel_hi:[1,0]
	v_pk_add_f32 v[148:149], v[148:149], 1.0 op_sel_hi:[1,0]
	v_pk_add_f32 v[150:151], v[150:151], 1.0 op_sel_hi:[1,0]
	v_pk_add_f32 v[152:153], v[152:153], 1.0 op_sel_hi:[1,0]
	v_rcp_f32_e32 v146, v146
	v_rcp_f32_e32 v147, v147
	v_rcp_f32_e32 v148, v148
	v_rcp_f32_e32 v149, v149
	v_rcp_f32_e32 v150, v150
	v_rcp_f32_e32 v151, v151
	v_rcp_f32_e32 v152, v152
	v_rcp_f32_e32 v153, v153
	v_pk_mul_f32 v[28:29], v[28:29], v[146:147]
	v_pk_mul_f32 v[30:31], v[30:31], v[148:149]
	v_pk_mul_f32 v[20:21], v[20:21], v[150:151]
	v_pk_mul_f32 v[22:23], v[22:23], v[152:153]
	v_pk_mul_f32 v[24:25], v[24:25], v[28:29]
	v_pk_mul_f32 v[26:27], v[26:27], v[30:31]
	v_pk_mul_f32 v[16:17], v[16:17], v[20:21]
	v_pk_mul_f32 v[18:19], v[18:19], v[22:23]
	v_cvt_pk_bf16_f32 v154, v24, v25
	v_cvt_pk_bf16_f32 v156, v16, v17
	v_cvt_pk_bf16_f32 v155, v26, v27
	v_cvt_pk_bf16_f32 v157, v18, v19
	global_store_dwordx2 v166, v[154:155], s[18:19]
	global_store_dwordx2 v166, v[156:157], s[18:19] offset:128
	v_pk_mul_f32 v[146:147], v[12:13], v[172:173]
	v_pk_mul_f32 v[148:149], v[14:15], v[172:173]
	v_pk_mul_f32 v[150:151], v[4:5], v[172:173]
	v_pk_mul_f32 v[152:153], v[6:7], v[172:173]
	v_exp_f32_e32 v146, v146
	v_exp_f32_e32 v147, v147
	v_exp_f32_e32 v148, v148
	v_exp_f32_e32 v149, v149
	v_exp_f32_e32 v150, v150
	v_exp_f32_e32 v151, v151
	v_exp_f32_e32 v152, v152
	v_exp_f32_e32 v153, v153
	v_pk_add_f32 v[146:147], v[146:147], 1.0 op_sel_hi:[1,0]
	v_pk_add_f32 v[148:149], v[148:149], 1.0 op_sel_hi:[1,0]
	v_pk_add_f32 v[150:151], v[150:151], 1.0 op_sel_hi:[1,0]
	v_pk_add_f32 v[152:153], v[152:153], 1.0 op_sel_hi:[1,0]
	v_rcp_f32_e32 v146, v146
	v_rcp_f32_e32 v147, v147
	v_rcp_f32_e32 v148, v148
	v_rcp_f32_e32 v149, v149
	v_rcp_f32_e32 v150, v150
	v_rcp_f32_e32 v151, v151
	v_rcp_f32_e32 v152, v152
	v_rcp_f32_e32 v153, v153
	v_pk_mul_f32 v[12:13], v[12:13], v[146:147]
	v_pk_mul_f32 v[14:15], v[14:15], v[148:149]
	v_pk_mul_f32 v[4:5], v[4:5], v[150:151]
	v_pk_mul_f32 v[6:7], v[6:7], v[152:153]
	v_pk_mul_f32 v[8:9], v[8:9], v[12:13]
	v_pk_mul_f32 v[10:11], v[10:11], v[14:15]
	v_pk_mul_f32 v[0:1], v[0:1], v[4:5]
	v_pk_mul_f32 v[2:3], v[2:3], v[6:7]
	v_cvt_pk_bf16_f32 v168, v8, v9
	v_cvt_pk_bf16_f32 v170, v0, v1
	v_cvt_pk_bf16_f32 v169, v10, v11
	v_cvt_pk_bf16_f32 v171, v2, v3
	global_store_dwordx2 v167, v[168:169], s[18:19]
	global_store_dwordx2 v167, v[170:171], s[18:19] offset:128
	s_andn2_b64 vcc, exec, s[54:55]
	s_mov_b64 s[2:3], -1
	s_cbranch_vccnz .LBB0_39

; #define PG8_BAR __builtin_amdgcn_s_barrier()
; template <class Epi, class Sched, bool ALIGN_EPI = false, bool SP2 = false>
; __device__ __forceinline__ void gemm_phase(PG8_LAS unsigned char* lds, const Gemm g, const Sched& S, const Epi& E) {
;     ...
;         if (!has_next) break;
; #pragma unroll
;         for (int a = 0; a < 2; ++a)
; #pragma unroll
;             for (int b = 0; b < 2; ++b)
; #pragma unroll
;                 for (int m = 0; m < 4; ++m)
; #pragma unroll
;                     for (int n = 0; n < 2; ++n) acc[a][b][m][n] = (f32x4){0.f, 0.f, 0.f, 0.f};
;         cur = nxt; cA = nA; cB = nB; ++ui;
;         if constexpr (ALIGN_EPI) { if (wr == 1) PG8_BAR; }
	s_andn2_b64 vcc, exec, s[38:39]
	s_cbranch_vccnz .LBB0_38
	s_barrier
	s_branch .LBB0_38
